# B-bf16 K-loop: spurious s_waitcnt vmcnt(0) drain (and mid-read lgkmcnt(0)) removed from the steady-state body; kept in the peeled first iteration
# speedup vs baseline: 1.0097x; 1.0097x over previous
; #define PG8_STAGE(bufoff, gbase, voff) do { _Pragma("unroll") for (int _i = 0; _i < 2; ++_i) \
;         __builtin_amdgcn_global_load_lds((const unsigned*)((const char*)(gbase) + (voff)[_i]), (PG8_LAS unsigned*)(lds + (bufoff) + ldsw + _i * 8192), 16, 0, 0); } while (0)
; #define PG8_LDA(dst, b, h) do { _Pragma("unroll") for (int m = 0; m < 4; ++m) _Pragma("unroll") for (int k = 0; k < 2; ++k) dst[m][k] = *(const PG8_LAS bf16x8*)(lds + PG8_SA(b, h) + aoff + m * 2048 + k * 1024); } while (0)
; #define PG8_LDB(dst, b, h) do { _Pragma("unroll") for (int n = 0; n < 2; ++n) _Pragma("unroll") for (int k = 0; k < 2; ++k) dst[n][k] = *(const PG8_LAS bf16x8*)(lds + PG8_SB(b, h) + boff + n * 2048 + k * 1024); } while (0)
; #define PG8_WAIT_V(n) asm volatile("s_waitcnt vmcnt(" #n ")" ::: "memory")
; #define PG8_WAIT_L(n) asm volatile("s_waitcnt lgkmcnt(" #n ")" ::: "memory")
; #define PG8_BAR __builtin_amdgcn_s_barrier()
; #define PG8_SCHED __builtin_amdgcn_sched_barrier(0)
; template <class Epi, class Sched, bool ALIGN_EPI = false, bool SP2 = false, bool I8 = false>
; __device__ __forceinline__ void gemm_phase(PG8_LAS unsigned char* lds, const Gemm g, const Sched& S, const Epi& E) {
;     ...
;             PG8_LDB(B0, 0, 0); PG8_LDB(B1, 0, 1); PG8_SCHED; PG8_LDA(At, 0, 0); PG8_STAGE(PG8_SA(1, 1), a1 + hstep, voffA);
;             PG8_WAIT_V(8); PG8_WAIT_L(0); PG8_BAR; PG8_MMA(0, 0, At, B0); PG8_MMA(0, 1, At, B1); PG8_BAR; PG8_SCHED;
;             PG8_LDA(At, 0, 1); PG8_STAGE(PG8_SB(0, 0), b2, voffB); PG8_STAGE(PG8_SB(0, 1), b2 + hstep, voffB); PG8_STAGE(PG8_SA(0, 0), a2, voffA);
;             PG8_WAIT_V(8); PG8_WAIT_L(0); PG8_BAR; PG8_MMA(1, 0, At, B0); PG8_MMA(1, 1, At, B1); PG8_BAR; PG8_SCHED;
.LBB0_230:
	s_add_u32 s50, s12, 0xfff00080
	s_addc_u32 s51, s13, -1
	s_add_i32 s56, 0, 0x10000
	s_cmp_eq_u32 s97, 60
	s_cselect_b32 s77, s11, s51
	s_cselect_b32 s76, s34, s50
	s_cselect_b32 s73, s27, s61
	s_cselect_b32 s72, s35, s37
	s_add_i32 s57, 0, 0x14000
	v_add_u32_e32 v156, s56, v171
	v_add_u32_e32 v168, s57, v171
	ds_read_b128 v[112:115], v156
	ds_read_b128 v[120:123], v156 offset:1024
	ds_read_b128 v[152:155], v156 offset:2048
	ds_read_b128 v[156:159], v156 offset:3072
	ds_read_b128 v[160:163], v168
	ds_read_b128 v[164:167], v168 offset:1024
	ds_read_b128 v[176:179], v168 offset:2048
	ds_read_b128 v[180:183], v168 offset:3072
	v_lshl_add_u64 v[168:169], s[12:13], 0, v[148:149]
	s_add_i32 m0, s47, 0xc000
	ds_read_b128 v[184:187], v173
	ds_read_b128 v[188:191], v173 offset:1024
	ds_read_b128 v[204:207], v173 offset:2048
	ds_read_b128 v[208:211], v173 offset:3072
	ds_read_b128 v[212:215], v173 offset:4096
	ds_read_b128 v[216:219], v173 offset:5120
	ds_read_b128 v[220:223], v173 offset:6144
	ds_read_b128 v[224:227], v173 offset:7168
	global_load_lds_dwordx4 v[168:169], off
	v_lshl_add_u64 v[168:169], s[12:13], 0, v[150:151]
	s_add_i32 m0, s47, 0xe000
	s_nop 0
	global_load_lds_dwordx4 v[168:169], off
	s_waitcnt vmcnt(8)
	s_waitcnt lgkmcnt(0)
	s_barrier
	s_setprio 1
	s_waitcnt lgkmcnt(0)
	v_mfma_f32_16x16x32_bf16 v[136:139], v[112:115], v[184:187], v[136:139]
	v_mfma_f32_16x16x32_bf16 v[136:139], v[120:123], v[188:191], v[136:139]
	v_mfma_f32_16x16x32_bf16 v[116:119], v[120:123], v[208:211], v[116:119]
	v_mfma_f32_16x16x32_bf16 v[116:119], v[112:115], v[204:207], v[116:119]
	v_mfma_f32_16x16x32_bf16 v[96:99], v[112:115], v[212:215], v[96:99]
	v_mfma_f32_16x16x32_bf16 v[96:99], v[120:123], v[216:219], v[96:99]
	v_mfma_f32_16x16x32_bf16 v[80:83], v[120:123], v[224:227], v[80:83]
	v_mfma_f32_16x16x32_bf16 v[80:83], v[112:115], v[220:223], v[80:83]
	v_mfma_f32_16x16x32_bf16 v[76:79], v[152:155], v[220:223], v[76:79]
	v_mfma_f32_16x16x32_bf16 v[76:79], v[156:159], v[224:227], v[76:79]
	v_mfma_f32_16x16x32_bf16 v[92:95], v[156:159], v[216:219], v[92:95]
	v_mfma_f32_16x16x32_bf16 v[92:95], v[152:155], v[212:215], v[92:95]
	v_mfma_f32_16x16x32_bf16 v[108:111], v[152:155], v[204:207], v[108:111]
	v_mfma_f32_16x16x32_bf16 v[108:111], v[156:159], v[208:211], v[108:111]
	v_mfma_f32_16x16x32_bf16 v[132:135], v[156:159], v[188:191], v[132:135]
	v_mfma_f32_16x16x32_bf16 v[132:135], v[152:155], v[184:187], v[132:135]
	v_mfma_f32_16x16x32_bf16 v[128:131], v[160:163], v[184:187], v[128:131]
	v_mfma_f32_16x16x32_bf16 v[128:131], v[164:167], v[188:191], v[128:131]
	v_mfma_f32_16x16x32_bf16 v[104:107], v[164:167], v[208:211], v[104:107]
	v_mfma_f32_16x16x32_bf16 v[104:107], v[160:163], v[204:207], v[104:107]
	v_mfma_f32_16x16x32_bf16 v[88:91], v[160:163], v[212:215], v[88:91]
	v_mfma_f32_16x16x32_bf16 v[88:91], v[164:167], v[216:219], v[88:91]
	v_mfma_f32_16x16x32_bf16 v[72:75], v[164:167], v[224:227], v[72:75]
	v_mfma_f32_16x16x32_bf16 v[72:75], v[160:163], v[220:223], v[72:75]
	v_mfma_f32_16x16x32_bf16 v[68:71], v[176:179], v[220:223], v[68:71]
	v_mfma_f32_16x16x32_bf16 v[68:71], v[180:183], v[224:227], v[68:71]
	v_mfma_f32_16x16x32_bf16 v[84:87], v[180:183], v[216:219], v[84:87]
	v_mfma_f32_16x16x32_bf16 v[84:87], v[176:179], v[212:215], v[84:87]
	v_mfma_f32_16x16x32_bf16 v[100:103], v[176:179], v[204:207], v[100:103]
	v_mfma_f32_16x16x32_bf16 v[100:103], v[180:183], v[208:211], v[100:103]
	v_mfma_f32_16x16x32_bf16 v[124:127], v[180:183], v[188:191], v[124:127]
	v_mfma_f32_16x16x32_bf16 v[124:127], v[176:179], v[184:187], v[124:127]
	s_setprio 0
	s_barrier
	s_add_i32 s50, s56, s46
	v_lshl_add_u64 v[168:169], s[72:73], 0, v[2:3]
	s_mov_b32 m0, s50
	ds_read_b128 v[184:187], v173 offset:16384
	ds_read_b128 v[188:191], v173 offset:17408
	ds_read_b128 v[204:207], v173 offset:18432
	ds_read_b128 v[208:211], v173 offset:19456
	ds_read_b128 v[212:215], v173 offset:20480
	ds_read_b128 v[216:219], v173 offset:21504
	ds_read_b128 v[220:223], v173 offset:22528
	ds_read_b128 v[224:227], v173 offset:23552
	global_load_lds_dwordx4 v[168:169], off
	s_add_i32 m0, s50, 0x2000
	s_add_u32 s50, s72, 0x100000
	v_lshl_add_u64 v[228:229], s[72:73], 0, v[144:145]
	s_addc_u32 s51, s73, 0
	s_add_i32 s56, s57, s46
	global_load_lds_dwordx4 v[228:229], off
	v_lshl_add_u64 v[240:241], s[50:51], 0, v[2:3]
	s_mov_b32 m0, s56
	v_lshl_add_u64 v[242:243], s[76:77], 0, v[142:143]
	global_load_lds_dwordx4 v[240:241], off
	v_lshl_add_u64 v[240:241], s[50:51], 0, v[144:145]
	s_add_i32 m0, s56, 0x2000
	s_nop 0
	global_load_lds_dwordx4 v[240:241], off
	v_lshl_add_u64 v[240:241], s[76:77], 0, v[140:141]
	s_mov_b32 m0, s47
	s_nop 0
	global_load_lds_dwordx4 v[240:241], off
	s_mov_b32 m0, s52
	s_nop 0
	global_load_lds_dwordx4 v[242:243], off
	s_waitcnt vmcnt(8)
	s_waitcnt lgkmcnt(0)
	s_barrier
; #define PG8_STAGE(bufoff, gbase, voff) do { _Pragma("unroll") for (int _i = 0; _i < 2; ++_i) \
;         __builtin_amdgcn_global_load_lds((const unsigned*)((const char*)(gbase) + (voff)[_i]), (PG8_LAS unsigned*)(lds + (bufoff) + ldsw + _i * 8192), 16, 0, 0); } while (0)
; #define PG8_LDA(dst, b, h) do { _Pragma("unroll") for (int m = 0; m < 4; ++m) _Pragma("unroll") for (int k = 0; k < 2; ++k) dst[m][k] = *(const PG8_LAS bf16x8*)(lds + PG8_SA(b, h) + aoff + m * 2048 + k * 1024); } while (0)
; #define PG8_LDB(dst, b, h) do { _Pragma("unroll") for (int n = 0; n < 2; ++n) _Pragma("unroll") for (int k = 0; k < 2; ++k) dst[n][k] = *(const PG8_LAS bf16x8*)(lds + PG8_SB(b, h) + boff + n * 2048 + k * 1024); } while (0)
; #define PG8_WAIT_V(n) asm volatile("s_waitcnt vmcnt(" #n ")" ::: "memory")
; #define PG8_WAIT_L(n) asm volatile("s_waitcnt lgkmcnt(" #n ")" ::: "memory")
; #define PG8_BAR __builtin_amdgcn_s_barrier()
; #define PG8_SCHED __builtin_amdgcn_sched_barrier(0)
; template <class Epi, class Sched, bool ALIGN_EPI = false, bool SP2 = false, bool I8 = false>
; __device__ __forceinline__ void gemm_phase(PG8_LAS unsigned char* lds, const Gemm g, const Sched& S, const Epi& E) {
;     ...
;             PG8_WAIT_V(8); PG8_WAIT_L(0); PG8_BAR; PG8_MMA(1, 0, At, B0); PG8_MMA(1, 1, At, B1); PG8_BAR; PG8_SCHED;
;             PG8_LDB(B0, 1, 0); PG8_LDB(B1, 1, 1); PG8_SCHED; PG8_LDA(At, 1, 0); PG8_STAGE(PG8_SA(0, 1), a2 + hstep, voffA);
;             PG8_WAIT_V(8); PG8_WAIT_L(0); PG8_BAR; PG8_MMA(0, 0, At, B0); PG8_MMA(0, 1, At, B1); PG8_BAR; PG8_SCHED;
	s_setprio 1
	s_waitcnt lgkmcnt(0)
	v_mfma_f32_16x16x32_bf16 v[64:67], v[112:115], v[184:187], v[64:67]
	v_mfma_f32_16x16x32_bf16 v[64:67], v[120:123], v[188:191], v[64:67]
	v_mfma_f32_16x16x32_bf16 v[48:51], v[120:123], v[208:211], v[48:51]
	v_mfma_f32_16x16x32_bf16 v[48:51], v[112:115], v[204:207], v[48:51]
	v_mfma_f32_16x16x32_bf16 v[32:35], v[112:115], v[212:215], v[32:35]
	v_mfma_f32_16x16x32_bf16 v[32:35], v[120:123], v[216:219], v[32:35]
	v_mfma_f32_16x16x32_bf16 v[16:19], v[120:123], v[224:227], v[16:19]
	v_mfma_f32_16x16x32_bf16 v[16:19], v[112:115], v[220:223], v[16:19]
	v_mfma_f32_16x16x32_bf16 v[12:15], v[152:155], v[220:223], v[12:15]
	v_mfma_f32_16x16x32_bf16 v[12:15], v[156:159], v[224:227], v[12:15]
	v_mfma_f32_16x16x32_bf16 v[28:31], v[156:159], v[216:219], v[28:31]
	v_mfma_f32_16x16x32_bf16 v[28:31], v[152:155], v[212:215], v[28:31]
	v_mfma_f32_16x16x32_bf16 v[44:47], v[152:155], v[204:207], v[44:47]
	v_mfma_f32_16x16x32_bf16 v[44:47], v[156:159], v[208:211], v[44:47]
	v_mfma_f32_16x16x32_bf16 v[60:63], v[156:159], v[188:191], v[60:63]
	v_mfma_f32_16x16x32_bf16 v[60:63], v[152:155], v[184:187], v[60:63]
	v_mfma_f32_16x16x32_bf16 v[56:59], v[160:163], v[184:187], v[56:59]
	v_mfma_f32_16x16x32_bf16 v[56:59], v[164:167], v[188:191], v[56:59]
	v_mfma_f32_16x16x32_bf16 v[40:43], v[164:167], v[208:211], v[40:43]
	v_mfma_f32_16x16x32_bf16 v[40:43], v[160:163], v[204:207], v[40:43]
	v_mfma_f32_16x16x32_bf16 v[24:27], v[160:163], v[212:215], v[24:27]
	v_mfma_f32_16x16x32_bf16 v[24:27], v[164:167], v[216:219], v[24:27]
	v_mfma_f32_16x16x32_bf16 v[8:11], v[164:167], v[224:227], v[8:11]
	v_mfma_f32_16x16x32_bf16 v[8:11], v[160:163], v[220:223], v[8:11]
	v_mfma_f32_16x16x32_bf16 v[4:7], v[176:179], v[220:223], v[4:7]
	v_mfma_f32_16x16x32_bf16 v[4:7], v[180:183], v[224:227], v[4:7]
	v_mfma_f32_16x16x32_bf16 v[20:23], v[180:183], v[216:219], v[20:23]
	v_mfma_f32_16x16x32_bf16 v[20:23], v[176:179], v[212:215], v[20:23]
	v_mfma_f32_16x16x32_bf16 v[36:39], v[176:179], v[204:207], v[36:39]
	v_mfma_f32_16x16x32_bf16 v[36:39], v[180:183], v[208:211], v[36:39]
	v_mfma_f32_16x16x32_bf16 v[52:55], v[180:183], v[188:191], v[52:55]
	v_mfma_f32_16x16x32_bf16 v[52:55], v[176:179], v[184:187], v[52:55]
	s_setprio 0
	s_barrier
	s_add_i32 s56, 0, 0x18000
	s_add_i32 s57, 0, 0x1c000
	v_add_u32_e32 v156, s56, v171
	v_add_u32_e32 v175, s57, v171
	ds_read_b128 v[112:115], v156
	ds_read_b128 v[120:123], v156 offset:1024
	ds_read_b128 v[152:155], v156 offset:2048
	ds_read_b128 v[156:159], v156 offset:3072
	ds_read_b128 v[160:163], v175
	ds_read_b128 v[164:167], v175 offset:1024
	ds_read_b128 v[176:179], v175 offset:2048
	ds_read_b128 v[180:183], v175 offset:3072
	s_add_u32 s50, s76, 0x100000
	s_addc_u32 s51, s77, 0
	s_mov_b32 m0, s53
	v_lshl_add_u64 v[244:245], s[50:51], 0, v[140:141]
	ds_read_b128 v[184:187], v173 offset:32768
	ds_read_b128 v[188:191], v173 offset:33792
	ds_read_b128 v[204:207], v173 offset:34816
	ds_read_b128 v[208:211], v173 offset:35840
	ds_read_b128 v[212:215], v173 offset:36864
	ds_read_b128 v[216:219], v173 offset:37888
	ds_read_b128 v[220:223], v173 offset:38912
	ds_read_b128 v[224:227], v173 offset:39936
	global_load_lds_dwordx4 v[244:245], off
	v_lshl_add_u64 v[244:245], s[50:51], 0, v[142:143]
	s_mov_b32 m0, s64
	s_nop 0
	global_load_lds_dwordx4 v[244:245], off
	s_waitcnt vmcnt(8)
	s_waitcnt lgkmcnt(0)
	s_barrier
	s_setprio 1
	s_waitcnt lgkmcnt(0)
	v_mfma_f32_16x16x32_bf16 v[136:139], v[112:115], v[184:187], v[136:139]
	v_mfma_f32_16x16x32_bf16 v[136:139], v[120:123], v[188:191], v[136:139]
	v_mfma_f32_16x16x32_bf16 v[116:119], v[120:123], v[208:211], v[116:119]
	v_mfma_f32_16x16x32_bf16 v[116:119], v[112:115], v[204:207], v[116:119]
	v_mfma_f32_16x16x32_bf16 v[96:99], v[112:115], v[212:215], v[96:99]
	v_mfma_f32_16x16x32_bf16 v[96:99], v[120:123], v[216:219], v[96:99]
	v_mfma_f32_16x16x32_bf16 v[80:83], v[120:123], v[224:227], v[80:83]
	v_mfma_f32_16x16x32_bf16 v[80:83], v[112:115], v[220:223], v[80:83]
	v_mfma_f32_16x16x32_bf16 v[76:79], v[152:155], v[220:223], v[76:79]
	v_mfma_f32_16x16x32_bf16 v[76:79], v[156:159], v[224:227], v[76:79]
	v_mfma_f32_16x16x32_bf16 v[92:95], v[156:159], v[216:219], v[92:95]
	v_mfma_f32_16x16x32_bf16 v[92:95], v[152:155], v[212:215], v[92:95]
	v_mfma_f32_16x16x32_bf16 v[108:111], v[152:155], v[204:207], v[108:111]
	v_mfma_f32_16x16x32_bf16 v[108:111], v[156:159], v[208:211], v[108:111]
	v_mfma_f32_16x16x32_bf16 v[132:135], v[156:159], v[188:191], v[132:135]
	v_mfma_f32_16x16x32_bf16 v[132:135], v[152:155], v[184:187], v[132:135]
	v_mfma_f32_16x16x32_bf16 v[128:131], v[160:163], v[184:187], v[128:131]
	v_mfma_f32_16x16x32_bf16 v[128:131], v[164:167], v[188:191], v[128:131]
	v_mfma_f32_16x16x32_bf16 v[104:107], v[164:167], v[208:211], v[104:107]
	v_mfma_f32_16x16x32_bf16 v[104:107], v[160:163], v[204:207], v[104:107]
	v_mfma_f32_16x16x32_bf16 v[88:91], v[160:163], v[212:215], v[88:91]
	v_mfma_f32_16x16x32_bf16 v[88:91], v[164:167], v[216:219], v[88:91]
	v_mfma_f32_16x16x32_bf16 v[72:75], v[164:167], v[224:227], v[72:75]
	v_mfma_f32_16x16x32_bf16 v[72:75], v[160:163], v[220:223], v[72:75]
	v_mfma_f32_16x16x32_bf16 v[68:71], v[176:179], v[220:223], v[68:71]
	v_mfma_f32_16x16x32_bf16 v[68:71], v[180:183], v[224:227], v[68:71]
	v_mfma_f32_16x16x32_bf16 v[84:87], v[180:183], v[216:219], v[84:87]
	v_mfma_f32_16x16x32_bf16 v[84:87], v[176:179], v[212:215], v[84:87]
	v_mfma_f32_16x16x32_bf16 v[100:103], v[176:179], v[204:207], v[100:103]
	v_mfma_f32_16x16x32_bf16 v[100:103], v[180:183], v[208:211], v[100:103]
	v_mfma_f32_16x16x32_bf16 v[124:127], v[180:183], v[188:191], v[124:127]
	v_mfma_f32_16x16x32_bf16 v[124:127], v[176:179], v[184:187], v[124:127]
	s_setprio 0
	s_barrier
; #define PG8_STAGE(bufoff, gbase, voff) do { _Pragma("unroll") for (int _i = 0; _i < 2; ++_i) \
;         __builtin_amdgcn_global_load_lds((const unsigned*)((const char*)(gbase) + (voff)[_i]), (PG8_LAS unsigned*)(lds + (bufoff) + ldsw + _i * 8192), 16, 0, 0); } while (0)
; #define PG8_LDA(dst, b, h) do { _Pragma("unroll") for (int m = 0; m < 4; ++m) _Pragma("unroll") for (int k = 0; k < 2; ++k) dst[m][k] = *(const PG8_LAS bf16x8*)(lds + PG8_SA(b, h) + aoff + m * 2048 + k * 1024); } while (0)
; #define PG8_WAIT_V(n) asm volatile("s_waitcnt vmcnt(" #n ")" ::: "memory")
; #define PG8_WAIT_L(n) asm volatile("s_waitcnt lgkmcnt(" #n ")" ::: "memory")
; #define PG8_BAR __builtin_amdgcn_s_barrier()
; #define PG8_SCHED __builtin_amdgcn_sched_barrier(0)
; template <class Epi, class Sched, bool ALIGN_EPI = false, bool SP2 = false, bool I8 = false>
; __device__ __forceinline__ void gemm_phase(PG8_LAS unsigned char* lds, const Gemm g, const Sched& S, const Epi& E) {
;     ...
;         for (int t = 0; t < nt; t += 2) {
;     ...
;             PG8_LDA(At, 1, 1); PG8_STAGE(PG8_SB(1, 0), b3, voffB); PG8_STAGE(PG8_SB(1, 1), b3 + hstep, voffB); PG8_STAGE(PG8_SA(1, 0), a3, voffA);
;             PG8_WAIT_V(8); PG8_WAIT_L(0); PG8_BAR; PG8_MMA(1, 0, At, B0); PG8_MMA(1, 1, At, B1); PG8_BAR; PG8_SCHED;
	s_add_i32 s50, s56, s46
	v_lshl_add_u64 v[168:169], v[168:169], 0, s[84:85]
	s_mov_b32 m0, s50
	ds_read_b128 v[184:187], v173 offset:49152
	ds_read_b128 v[188:191], v173 offset:50176
	ds_read_b128 v[204:207], v173 offset:51200
	ds_read_b128 v[208:211], v173 offset:52224
	ds_read_b128 v[212:215], v173 offset:53248
	ds_read_b128 v[216:219], v173 offset:54272
	ds_read_b128 v[220:223], v173 offset:55296
	ds_read_b128 v[224:227], v173 offset:56320
	global_load_lds_dwordx4 v[168:169], off
	s_add_i32 m0, s50, 0x2000
	s_add_u32 s50, s72, 0x100080
	v_lshl_add_u64 v[168:169], v[228:229], 0, s[84:85]
	s_addc_u32 s51, s73, 0
	s_add_i32 s56, s57, s46
	global_load_lds_dwordx4 v[168:169], off
	v_lshl_add_u64 v[168:169], s[50:51], 0, v[2:3]
	s_mov_b32 m0, s56
	s_nop 0
	global_load_lds_dwordx4 v[168:169], off
	v_lshl_add_u64 v[168:169], s[50:51], 0, v[144:145]
	s_add_i32 m0, s56, 0x2000
	s_nop 0
	global_load_lds_dwordx4 v[168:169], off
	v_lshl_add_u64 v[168:169], v[240:241], 0, s[84:85]
	s_mov_b32 m0, s28
	s_nop 0
	global_load_lds_dwordx4 v[168:169], off
	v_lshl_add_u64 v[168:169], v[242:243], 0, s[84:85]
	s_mov_b32 m0, s65
	s_nop 0
	global_load_lds_dwordx4 v[168:169], off
	s_waitcnt vmcnt(8)
	s_waitcnt lgkmcnt(0)
	s_barrier
	s_setprio 1
	s_waitcnt lgkmcnt(0)
	v_mfma_f32_16x16x32_bf16 v[64:67], v[112:115], v[184:187], v[64:67]
	v_mfma_f32_16x16x32_bf16 v[64:67], v[120:123], v[188:191], v[64:67]
	v_mfma_f32_16x16x32_bf16 v[48:51], v[120:123], v[208:211], v[48:51]
	v_mfma_f32_16x16x32_bf16 v[48:51], v[112:115], v[204:207], v[48:51]
	v_mfma_f32_16x16x32_bf16 v[32:35], v[112:115], v[212:215], v[32:35]
	v_mfma_f32_16x16x32_bf16 v[32:35], v[120:123], v[216:219], v[32:35]
	v_mfma_f32_16x16x32_bf16 v[16:19], v[120:123], v[224:227], v[16:19]
	v_mfma_f32_16x16x32_bf16 v[16:19], v[112:115], v[220:223], v[16:19]
	v_mfma_f32_16x16x32_bf16 v[12:15], v[152:155], v[220:223], v[12:15]
	v_mfma_f32_16x16x32_bf16 v[12:15], v[156:159], v[224:227], v[12:15]
	v_mfma_f32_16x16x32_bf16 v[28:31], v[156:159], v[216:219], v[28:31]
	v_mfma_f32_16x16x32_bf16 v[28:31], v[152:155], v[212:215], v[28:31]
	v_mfma_f32_16x16x32_bf16 v[44:47], v[152:155], v[204:207], v[44:47]
	v_mfma_f32_16x16x32_bf16 v[44:47], v[156:159], v[208:211], v[44:47]
	v_mfma_f32_16x16x32_bf16 v[60:63], v[156:159], v[188:191], v[60:63]
	v_mfma_f32_16x16x32_bf16 v[60:63], v[152:155], v[184:187], v[60:63]
	v_mfma_f32_16x16x32_bf16 v[56:59], v[160:163], v[184:187], v[56:59]
	v_mfma_f32_16x16x32_bf16 v[56:59], v[164:167], v[188:191], v[56:59]
	v_mfma_f32_16x16x32_bf16 v[40:43], v[164:167], v[208:211], v[40:43]
	v_mfma_f32_16x16x32_bf16 v[40:43], v[160:163], v[204:207], v[40:43]
	v_mfma_f32_16x16x32_bf16 v[24:27], v[160:163], v[212:215], v[24:27]
	v_mfma_f32_16x16x32_bf16 v[24:27], v[164:167], v[216:219], v[24:27]
	v_mfma_f32_16x16x32_bf16 v[8:11], v[164:167], v[224:227], v[8:11]
	v_mfma_f32_16x16x32_bf16 v[8:11], v[160:163], v[220:223], v[8:11]
	v_mfma_f32_16x16x32_bf16 v[4:7], v[176:179], v[220:223], v[4:7]
	v_mfma_f32_16x16x32_bf16 v[4:7], v[180:183], v[224:227], v[4:7]
	v_mfma_f32_16x16x32_bf16 v[20:23], v[180:183], v[216:219], v[20:23]
	v_mfma_f32_16x16x32_bf16 v[20:23], v[176:179], v[212:215], v[20:23]
	v_mfma_f32_16x16x32_bf16 v[36:39], v[176:179], v[204:207], v[36:39]
	v_mfma_f32_16x16x32_bf16 v[36:39], v[180:183], v[208:211], v[36:39]
	v_mfma_f32_16x16x32_bf16 v[52:55], v[180:183], v[188:191], v[52:55]
	v_mfma_f32_16x16x32_bf16 v[52:55], v[176:179], v[184:187], v[52:55]
	s_setprio 0
	s_barrier
	s_add_i32 s97, s97, 2
	s_add_u32 s12, s12, 0x100
	s_addc_u32 s13, s13, 0
	s_add_u32 s37, s37, 0x100
	s_addc_u32 s61, s61, 0
	s_cmp_gt_u32 s97, 61
	s_cbranch_scc0 .LBB0_230
